# P5 epilogue: first-half row-sum atomics deferred to the epilogue end (out of the in-order queue ahead of the second half's loads)
# speedup vs baseline: 1.0060x; 1.0039x over previous
.LBB0_707:
	s_or_b64 exec, exec, s[26:27]
	s_waitcnt vmcnt(0)
	v_pk_add_f32 v[128:129], v[128:129], v[164:165]
	v_pk_add_f32 v[126:127], v[126:127], v[162:163]
	v_pk_add_f32 v[140:141], v[124:125], v[140:141]
	v_pk_add_f32 v[124:125], v[122:123], v[138:139]
	v_mul_f32_e32 v122, v127, v127
	v_mul_f32_e32 v123, v129, v129
	v_fmac_f32_e32 v122, v126, v126
	v_fmac_f32_e32 v123, v128, v128
	v_add_f32_e32 v122, v122, v123
	v_mul_f32_e32 v123, v125, v125
	v_pk_add_f32 v[120:121], v[120:121], v[176:177]
	v_pk_add_f32 v[118:119], v[118:119], v[174:175]
	v_fmac_f32_e32 v123, v124, v124
	v_pk_add_f32 v[138:139], v[114:115], v[142:143]
	v_mul_f32_e32 v114, v119, v119
	v_mul_f32_e32 v115, v121, v121
	v_add_f32_e32 v122, v122, v123
	v_mul_f32_e32 v123, v141, v141
	v_fmac_f32_e32 v114, v118, v118
	v_fmac_f32_e32 v115, v120, v120
	v_fmac_f32_e32 v123, v140, v140
	v_add_f32_e32 v114, v114, v115
	v_mul_f32_e32 v115, v139, v139
	v_add_f32_e32 v162, v123, v122
	v_cvt_pk_bf16_f32 v123, v128, v129
	v_pk_add_f32 v[128:129], v[116:117], v[144:145]
	v_fmac_f32_e32 v115, v138, v138
	v_add_f32_e32 v114, v114, v115
	v_mul_f32_e32 v115, v129, v129
	v_fmac_f32_e32 v115, v128, v128
	v_and_b32_e32 v116, 64, v225
	v_cvt_pk_bf16_f32 v124, v124, v125
	v_cvt_pk_bf16_f32 v125, v140, v141
	v_add_f32_e32 v114, v115, v114
	v_xor_b32_e32 v115, 16, v225
	v_add_u32_e32 v140, 64, v116
	v_cmp_lt_i32_e64 s[10:11], v115, v140
	v_add_f32_e32 v114, v162, v114
	v_lshlrev_b64 v[218:219], 11, v[210:211]
	v_cndmask_b32_e64 v115, v225, v115, s[10:11]
	v_lshlrev_b32_e32 v142, 2, v115
	ds_bpermute_b32 v115, v142, v114
	v_cvt_pk_bf16_f32 v122, v126, v127
	v_lshl_add_u64 v[126:127], s[96:97], 0, v[218:219]
	v_lshl_add_u64 v[126:127], v[208:209], 1, v[126:127]
	v_cvt_pk_bf16_f32 v116, v118, v119
	s_waitcnt lgkmcnt(0)
	v_add_f32_e32 v114, v114, v115
	v_xor_b32_e32 v115, 32, v225
	v_cmp_lt_i32_e64 s[10:11], v115, v140
	v_cvt_pk_bf16_f32 v118, v138, v139
	v_lshl_add_u64 v[138:139], v[210:211], 2, s[76:77]
	global_store_dwordx4 v[126:127], v[122:125], off
	v_cndmask_b32_e64 v115, v225, v115, s[10:11]
	v_lshlrev_b32_e32 v143, 2, v115
	ds_bpermute_b32 v115, v143, v114
	v_cvt_pk_bf16_f32 v117, v120, v121
	v_cvt_pk_bf16_f32 v119, v128, v129
	global_store_dwordx4 v[126:127], v[116:119], off offset:256
	s_and_saveexec_b64 s[10:11], s[0:1]
	s_cbranch_execz .LBB0_709
	s_waitcnt lgkmcnt(0)
	v_add_f32_e32 v114, v114, v115
	v_mov_b32_e32 v248, v114
.LBB0_709:
	s_or_b64 exec, exec, s[10:11]
	v_pk_add_f32 v[112:113], v[112:113], v[156:157]
	v_pk_add_f32 v[110:111], v[110:111], v[154:155]
	v_pk_add_f32 v[116:117], v[108:109], v[132:133]
	v_pk_add_f32 v[108:109], v[106:107], v[130:131]
	v_mul_f32_e32 v106, v111, v111
	v_mul_f32_e32 v107, v113, v113
	v_fmac_f32_e32 v106, v110, v110
	v_fmac_f32_e32 v107, v112, v112
	v_add_f32_e32 v106, v106, v107
	v_mul_f32_e32 v107, v109, v109
	v_fmac_f32_e32 v107, v108, v108
	v_add_f32_e32 v106, v106, v107
	v_mul_f32_e32 v107, v117, v117
	v_fmac_f32_e32 v107, v116, v116
	v_pk_add_f32 v[104:105], v[104:105], v[160:161]
	v_pk_add_f32 v[102:103], v[102:103], v[158:159]
	v_add_f32_e32 v118, v107, v106
	v_cvt_pk_bf16_f32 v107, v112, v113
	v_pk_add_f32 v[112:113], v[98:99], v[134:135]
	v_mul_f32_e32 v98, v103, v103
	v_mul_f32_e32 v99, v105, v105
	v_fmac_f32_e32 v98, v102, v102
	v_fmac_f32_e32 v99, v104, v104
	v_add_f32_e32 v98, v98, v99
	v_mul_f32_e32 v99, v113, v113
	v_cvt_pk_bf16_f32 v106, v110, v111
	v_pk_add_f32 v[110:111], v[100:101], v[136:137]
	v_fmac_f32_e32 v99, v112, v112
	v_add_f32_e32 v98, v98, v99
	v_mul_f32_e32 v99, v111, v111
	v_fmac_f32_e32 v99, v110, v110
	v_add_f32_e32 v98, v99, v98
	v_add_f32_e32 v101, v118, v98
	v_cvt_pk_bf16_f32 v108, v108, v109
	v_cvt_pk_bf16_f32 v109, v116, v117
	ds_bpermute_b32 v116, v142, v101
	s_waitcnt lgkmcnt(1)
	v_lshlrev_b64 v[114:115], 11, v[212:213]
	v_lshl_add_u64 v[98:99], s[96:97], 0, v[114:115]
	v_lshl_add_u64 v[114:115], v[208:209], 1, v[98:99]
	global_store_dwordx4 v[114:115], v[106:109], off
	s_waitcnt lgkmcnt(0)
	v_add_f32_e32 v98, v101, v116
	ds_bpermute_b32 v99, v143, v98
	v_cvt_pk_bf16_f32 v100, v102, v103
	v_cvt_pk_bf16_f32 v101, v104, v105
	v_cvt_pk_bf16_f32 v102, v112, v113
	v_cvt_pk_bf16_f32 v103, v110, v111
	global_store_dwordx4 v[114:115], v[100:103], off offset:256
	s_and_saveexec_b64 s[10:11], s[0:1]
	s_cbranch_execz .LBB0_711
	s_waitcnt lgkmcnt(0)
	v_add_f32_e32 v98, v98, v99
	v_mov_b32_e32 v249, v98
.LBB0_711:
	s_or_b64 exec, exec, s[10:11]
	v_pk_add_f32 v[96:97], v[96:97], v[180:181]
	v_pk_add_f32 v[94:95], v[94:95], v[178:179]
	v_pk_add_f32 v[100:101], v[92:93], v[148:149]
	v_pk_add_f32 v[92:93], v[90:91], v[146:147]
	v_mul_f32_e32 v90, v95, v95
	v_mul_f32_e32 v91, v97, v97
	v_fmac_f32_e32 v90, v94, v94
	v_fmac_f32_e32 v91, v96, v96
	v_add_f32_e32 v90, v90, v91
	v_mul_f32_e32 v91, v93, v93
	v_fmac_f32_e32 v91, v92, v92
	v_add_f32_e32 v90, v90, v91
	v_mul_f32_e32 v91, v101, v101
	v_fmac_f32_e32 v91, v100, v100
	v_pk_add_f32 v[88:89], v[88:89], v[184:185]
	v_pk_add_f32 v[86:87], v[86:87], v[182:183]
	v_add_f32_e32 v102, v91, v90
	v_cvt_pk_bf16_f32 v91, v96, v97
	v_pk_add_f32 v[96:97], v[82:83], v[150:151]
	v_mul_f32_e32 v82, v87, v87
	v_mul_f32_e32 v83, v89, v89
	v_fmac_f32_e32 v82, v86, v86
	v_fmac_f32_e32 v83, v88, v88
	v_add_f32_e32 v82, v82, v83
	v_mul_f32_e32 v83, v97, v97
	v_cvt_pk_bf16_f32 v90, v94, v95
	v_pk_add_f32 v[94:95], v[84:85], v[152:153]
	v_fmac_f32_e32 v83, v96, v96
	v_add_f32_e32 v82, v82, v83
	v_mul_f32_e32 v83, v95, v95
	v_fmac_f32_e32 v83, v94, v94
	v_add_f32_e32 v82, v83, v82
	v_add_f32_e32 v85, v102, v82
	v_cvt_pk_bf16_f32 v92, v92, v93
	v_cvt_pk_bf16_f32 v93, v100, v101
	ds_bpermute_b32 v100, v142, v85
	s_waitcnt lgkmcnt(1)
	v_lshlrev_b64 v[98:99], 11, v[214:215]
	v_lshl_add_u64 v[82:83], s[96:97], 0, v[98:99]
	v_lshl_add_u64 v[98:99], v[208:209], 1, v[82:83]
	global_store_dwordx4 v[98:99], v[90:93], off
	s_waitcnt lgkmcnt(0)
	v_add_f32_e32 v82, v85, v100
	ds_bpermute_b32 v83, v143, v82
	v_cvt_pk_bf16_f32 v84, v86, v87
	v_cvt_pk_bf16_f32 v85, v88, v89
	v_cvt_pk_bf16_f32 v86, v96, v97
	v_cvt_pk_bf16_f32 v87, v94, v95
	global_store_dwordx4 v[98:99], v[84:87], off offset:256
	s_and_saveexec_b64 s[10:11], s[0:1]
	s_cbranch_execz .LBB0_713
	s_waitcnt lgkmcnt(0)
	v_add_f32_e32 v82, v82, v83
	v_mov_b32_e32 v250, v82
.LBB0_713:
	s_or_b64 exec, exec, s[10:11]
	v_pk_add_f32 v[80:81], v[80:81], v[188:189]
	v_pk_add_f32 v[78:79], v[78:79], v[186:187]
	v_pk_add_f32 v[84:85], v[76:77], v[168:169]
	v_pk_add_f32 v[76:77], v[74:75], v[166:167]
	v_mul_f32_e32 v74, v79, v79
	v_mul_f32_e32 v75, v81, v81
	v_fmac_f32_e32 v74, v78, v78
	v_fmac_f32_e32 v75, v80, v80
	v_add_f32_e32 v74, v74, v75
	v_mul_f32_e32 v75, v77, v77
	v_fmac_f32_e32 v75, v76, v76
	v_add_f32_e32 v74, v74, v75
	v_mul_f32_e32 v75, v85, v85
	v_fmac_f32_e32 v75, v84, v84
	v_pk_add_f32 v[72:73], v[72:73], v[192:193]
	v_pk_add_f32 v[70:71], v[70:71], v[190:191]
	v_add_f32_e32 v86, v75, v74
	v_cvt_pk_bf16_f32 v75, v80, v81
	v_pk_add_f32 v[80:81], v[66:67], v[170:171]
	v_mul_f32_e32 v66, v71, v71
	v_mul_f32_e32 v67, v73, v73
	v_fmac_f32_e32 v66, v70, v70
	v_fmac_f32_e32 v67, v72, v72
	v_add_f32_e32 v66, v66, v67
	v_mul_f32_e32 v67, v81, v81
	v_cvt_pk_bf16_f32 v74, v78, v79
	v_pk_add_f32 v[78:79], v[68:69], v[172:173]
	v_fmac_f32_e32 v67, v80, v80
	v_add_f32_e32 v66, v66, v67
	v_mul_f32_e32 v67, v79, v79
	v_fmac_f32_e32 v67, v78, v78
	v_add_f32_e32 v66, v67, v66
	v_add_f32_e32 v69, v86, v66
	v_cvt_pk_bf16_f32 v76, v76, v77
	v_cvt_pk_bf16_f32 v77, v84, v85
	ds_bpermute_b32 v84, v142, v69
	s_waitcnt lgkmcnt(1)
	v_lshlrev_b64 v[82:83], 11, v[216:217]
	v_lshl_add_u64 v[66:67], s[96:97], 0, v[82:83]
	v_lshl_add_u64 v[82:83], v[208:209], 1, v[66:67]
	global_store_dwordx4 v[82:83], v[74:77], off
	s_waitcnt lgkmcnt(0)
	v_add_f32_e32 v66, v69, v84
	ds_bpermute_b32 v67, v143, v66
	v_cvt_pk_bf16_f32 v68, v70, v71
	v_cvt_pk_bf16_f32 v69, v72, v73
	v_cvt_pk_bf16_f32 v70, v80, v81
	v_cvt_pk_bf16_f32 v71, v78, v79
	global_store_dwordx4 v[82:83], v[68:71], off offset:256
	s_and_saveexec_b64 s[10:11], s[0:1]
	s_cbranch_execz .LBB0_715
	s_waitcnt lgkmcnt(0)
	v_add_f32_e32 v66, v66, v67
	v_mov_b32_e32 v251, v66

.LBB0_753:
	s_or_b64 exec, exec, s[4:5]
	v_pk_add_f32 v[16:17], v[16:17], v[124:125]
	v_pk_add_f32 v[14:15], v[14:15], v[122:123]
	v_pk_add_f32 v[20:21], v[12:13], v[100:101]
	v_pk_add_f32 v[12:13], v[10:11], v[98:99]
	v_mul_f32_e32 v10, v15, v15
	v_mul_f32_e32 v11, v17, v17
	v_fmac_f32_e32 v10, v14, v14
	v_fmac_f32_e32 v11, v16, v16
	v_add_f32_e32 v10, v10, v11
	v_mul_f32_e32 v11, v13, v13
	v_fmac_f32_e32 v11, v12, v12
	v_add_f32_e32 v10, v10, v11
	v_mul_f32_e32 v11, v21, v21
	v_fmac_f32_e32 v11, v20, v20
	v_pk_add_f32 v[8:9], v[8:9], v[128:129]
	v_pk_add_f32 v[6:7], v[6:7], v[126:127]
	v_add_f32_e32 v22, v11, v10
	v_cvt_pk_bf16_f32 v11, v16, v17
	v_pk_add_f32 v[16:17], v[2:3], v[106:107]
	v_mul_f32_e32 v2, v7, v7
	v_mul_f32_e32 v3, v9, v9
	v_fmac_f32_e32 v2, v6, v6
	v_fmac_f32_e32 v3, v8, v8
	v_add_f32_e32 v2, v2, v3
	v_mul_f32_e32 v3, v17, v17
	v_cvt_pk_bf16_f32 v10, v14, v15
	v_pk_add_f32 v[14:15], v[4:5], v[108:109]
	v_fmac_f32_e32 v3, v16, v16
	v_add_f32_e32 v2, v2, v3
	v_mul_f32_e32 v3, v15, v15
	v_fmac_f32_e32 v3, v14, v14
	v_add_f32_e32 v2, v3, v2
	v_add_f32_e32 v5, v22, v2
	v_cvt_pk_bf16_f32 v12, v12, v13
	v_cvt_pk_bf16_f32 v13, v20, v21
	ds_bpermute_b32 v20, v142, v5
	s_waitcnt lgkmcnt(1)
	v_lshlrev_b64 v[18:19], 11, v[136:137]
	v_lshl_add_u64 v[2:3], s[96:97], 0, v[18:19]
	v_lshl_add_u64 v[18:19], v[208:209], 1, v[2:3]
	global_store_dwordx4 v[18:19], v[10:13], off
	s_waitcnt lgkmcnt(0)
	v_add_f32_e32 v2, v5, v20
	ds_bpermute_b32 v3, v143, v2
	v_cvt_pk_bf16_f32 v4, v6, v7
	v_cvt_pk_bf16_f32 v5, v8, v9
	v_cvt_pk_bf16_f32 v6, v16, v17
	v_cvt_pk_bf16_f32 v7, v14, v15
	global_store_dwordx4 v[18:19], v[4:7], off offset:256
	s_and_saveexec_b64 s[4:5], s[0:1]
	s_cbranch_execz .LBB0_755
	s_waitcnt lgkmcnt(0)
	v_add_f32_e32 v2, v2, v3
	global_atomic_add_f32 v[138:139], v2, off offset:704
	global_atomic_add_f32 v[138:139], v248, off
	global_atomic_add_f32 v[138:139], v249, off offset:64
	global_atomic_add_f32 v[138:139], v250, off offset:128
	global_atomic_add_f32 v[138:139], v251, off offset:192
